# attention queue order: pop the 128 sample items between prompt chunks c=34 and c=33 (longest-first) instead of last
# speedup vs baseline: 1.0255x; 1.0255x over previous
; DI int pop_block(int* ctr, int*) {
;   __syncthreads();
;   if (threadIdx.x == 0) sh_item = atomicAdd(ctr, 1);
;   __syncthreads();
;   return __builtin_amdgcn_readfirstlane(sh_item);
; }
; DI void phase_b2(const Params& p, int layer, char*, int*) {
;     ...
;   int* ctr2 = (int*)(p.ws + W_CTR) + layer * 4 + 2;
;   for (;;) {
;     int it = pop_block(ctr2, nullptr);
;     if (it >= 2208) break;
;     if (it < 2048) { const int c = 64 - (it >> 5), pair = it & 31; attn_block(p, 1, pair >> 3, c, pair & 7); }
;     else if (it < 2176) { const int r = it - 2048; attn_block(p, 0, r >> 3, 0, r & 7); }
;     else { const int pair = it - 2176; attn_block(p, 1, pair >> 3, 0, pair & 7); }
;   }
.LBB0_4834:
	s_barrier
	s_and_saveexec_b64 s[0:1], s[96:97]
	s_cbranch_execz .LBB0_4838
	v_mov_b32_e32 v1, 1
	global_atomic_add v1, v129, v1, s[38:39] offset:8 sc0
	s_waitcnt vmcnt(0)
	v_add_u32_e32 v0, 0x420, v1
	v_subrev_u32_e32 v2, 0x80, v1
	v_cmp_gt_u32_e32 vcc, 0x460, v1
	s_nop 1
	v_cndmask_b32_e32 v0, v2, v0, vcc
	v_cmp_gt_u32_e32 vcc, 0x3e0, v1
	s_nop 1
	v_cndmask_b32_e32 v0, v0, v1, vcc
	v_cmp_gt_u32_e32 vcc, 0x880, v1
	s_nop 1
	v_cndmask_b32_e32 v1, v1, v0, vcc
	ds_write_b32 v129, v1 offset:32
